# v80 + hand-written residual epilogues for the Wo and down GEMMs (counted waits, butterfly reduce-scatter of the row sums of squares, no ds_bpermute; down keeps the compiler path for the last layer)
# speedup vs baseline: 1.0035x; 1.0035x over previous
; __device__ __forceinline__ unsigned cvtpk(float lo, float hi) { f32x2 v = {lo, hi}; bf16x2_t b = __builtin_convertvector(v, bf16x2_t); return __builtin_bit_cast(unsigned, b); }
;     __device__ __forceinline__ void operator()(const f32x4 (&acc)[2][2][4][2], const Unit& u, int wr, int wc, int fr, int fq) const {
;         const int row0 = u.pm * BM + wr * 64 + fr;
;         const int col0 = u.pn * BM + wc * 32 + 8 * fq;
;         u32x4 w[2][4][2];
; #pragma unroll
;         for (int ai = 0; ai < 2; ++ai)
; #pragma unroll
;             for (int m = 0; m < 4; ++m)
; #pragma unroll
;                 for (int bj = 0; bj < 2; ++bj) w[ai][m][bj] = *(const u32x4*)(xb + (size_t)(row0 + ai * HALF + m * 16) * 1024 + col0 + bj * HALF);
; #pragma unroll
;         for (int ai = 0; ai < 2; ++ai)
; #pragma unroll
;             for (int m = 0; m < 4; ++m) {
;                 const int row = row0 + ai * HALF + m * 16;
;                 const size_t off = (size_t)row * 1024 + col0;
;                 float ss = 0.f;
; #pragma unroll
;                 for (int bj = 0; bj < 2; ++bj) {
;                     const u32x4 wv = w[ai][m][bj];
;                     f32x4 o0 = acc[ai][bj][m][0], o1 = acc[ai][bj][m][1];
;                     o0[0] += __builtin_bit_cast(float, wv.x << 16); o0[1] += __builtin_bit_cast(float, wv.x & 0xffff0000u); o0[2] += __builtin_bit_cast(float, wv.y << 16); o0[3] += __builtin_bit_cast(float, wv.y & 0xffff0000u);
;                     o1[0] += __builtin_bit_cast(float, wv.z << 16); o1[1] += __builtin_bit_cast(float, wv.z & 0xffff0000u); o1[2] += __builtin_bit_cast(float, wv.w << 16); o1[3] += __builtin_bit_cast(float, wv.w & 0xffff0000u);
;                     if (last) { *(f32x4*)(out + off + bj * HALF) = o0; *(f32x4*)(out + off + bj * HALF + 4) = o1; }
;                     else {
;                         u32x4 v; v.x = cvtpk(o0[0], o0[1]); v.y = cvtpk(o0[2], o0[3]); v.z = cvtpk(o1[0], o1[1]); v.w = cvtpk(o1[2], o1[3]);
;                         *(u32x4*)(xb + off + bj * HALF) = v;
;                         ss += (o0[0] * o0[0] + o0[1] * o0[1]) + (o0[2] * o0[2] + o0[3] * o0[3]) + (o1[0] * o1[0] + o1[1] * o1[1]) + (o1[2] * o1[2] + o1[3] * o1[3]);
.LBB0_332:
	v_lshl_add_u32 v212, s26, 8, v3
	v_lshl_or_b32 v213, s24, 8, v252
	v_lshlrev_b32_e32 v230, 1, v213
	v_lshl_add_u32 v230, v212, 11, v230
	v_mov_b32_e32 v231, v2
	s_mov_b32 s101, 0
	s_mov_b32 s28, 0xffff0000
	v_lshl_add_u64 v[214:215], s[10:11], 0, v[230:231]
	global_load_dwordx4 v[192:195], v[214:215], off
	global_load_dwordx4 v[188:191], v[214:215], off offset:256
	s_mov_b32 s100, 0x8000
	v_lshl_add_u64 v[216:217], v[214:215], 0, s[100:101]
	global_load_dwordx4 v[184:187], v[216:217], off
	global_load_dwordx4 v[180:183], v[216:217], off offset:256
	s_mov_b32 s100, 0x10000
	v_lshl_add_u64 v[218:219], v[214:215], 0, s[100:101]
	global_load_dwordx4 v[176:179], v[218:219], off
	global_load_dwordx4 v[172:175], v[218:219], off offset:256
	s_mov_b32 s100, 0x18000
	v_lshl_add_u64 v[220:221], v[214:215], 0, s[100:101]
	global_load_dwordx4 v[168:171], v[220:221], off
	global_load_dwordx4 v[164:167], v[220:221], off offset:256
	s_mov_b32 s100, 0x40000
	v_lshl_add_u64 v[222:223], v[214:215], 0, s[100:101]
	global_load_dwordx4 v[156:159], v[222:223], off
	global_load_dwordx4 v[148:151], v[222:223], off offset:256
	s_mov_b32 s100, 0x48000
	v_lshl_add_u64 v[224:225], v[214:215], 0, s[100:101]
	global_load_dwordx4 v[140:143], v[224:225], off
	global_load_dwordx4 v[132:135], v[224:225], off offset:256
	s_mov_b32 s100, 0x50000
	v_lshl_add_u64 v[226:227], v[214:215], 0, s[100:101]
	global_load_dwordx4 v[128:131], v[226:227], off
	global_load_dwordx4 v[112:115], v[226:227], off offset:256
	s_mov_b32 s100, 0x58000
	v_lshl_add_u64 v[228:229], v[214:215], 0, s[100:101]
	global_load_dwordx4 v[124:127], v[228:229], off
	global_load_dwordx4 v[108:111], v[228:229], off offset:256
	s_waitcnt vmcnt(14)
	v_lshlrev_b32_e32 v230, 16, v192
	v_and_b32_e32 v231, s28, v192
	v_lshlrev_b32_e32 v232, 16, v193
	v_and_b32_e32 v233, s28, v193
	v_lshlrev_b32_e32 v234, 16, v194
	v_and_b32_e32 v235, s28, v194
	v_lshlrev_b32_e32 v236, 16, v195
	v_and_b32_e32 v237, s28, v195
	v_pk_add_f32 v[160:161], v[160:161], v[230:231]
	v_pk_add_f32 v[162:163], v[162:163], v[232:233]
	v_pk_add_f32 v[152:153], v[152:153], v[234:235]
	v_pk_add_f32 v[154:155], v[154:155], v[236:237]
	v_cvt_pk_bf16_f32 v192, v160, v161
	v_cvt_pk_bf16_f32 v193, v162, v163
	v_cvt_pk_bf16_f32 v194, v152, v153
	v_cvt_pk_bf16_f32 v195, v154, v155
	global_store_dwordx4 v[214:215], v[192:195], off
	v_lshlrev_b32_e32 v230, 16, v188
	v_and_b32_e32 v231, s28, v188
	v_lshlrev_b32_e32 v232, 16, v189
	v_and_b32_e32 v233, s28, v189
	v_lshlrev_b32_e32 v234, 16, v190
	v_and_b32_e32 v235, s28, v190
	v_lshlrev_b32_e32 v236, 16, v191
	v_and_b32_e32 v237, s28, v191
	v_pk_add_f32 v[144:145], v[144:145], v[230:231]
	v_pk_add_f32 v[146:147], v[146:147], v[232:233]
	v_pk_add_f32 v[136:137], v[136:137], v[234:235]
	v_pk_add_f32 v[138:139], v[138:139], v[236:237]
	v_cvt_pk_bf16_f32 v188, v144, v145
	v_cvt_pk_bf16_f32 v189, v146, v147
	v_cvt_pk_bf16_f32 v190, v136, v137
	v_cvt_pk_bf16_f32 v191, v138, v139
	global_store_dwordx4 v[214:215], v[188:191], off offset:256
	v_pk_mul_f32 v[230:231], v[160:161], v[160:161]
	v_pk_mul_f32 v[232:233], v[162:163], v[162:163]
	v_pk_fma_f32 v[230:231], v[152:153], v[152:153], v[230:231]
	v_pk_fma_f32 v[232:233], v[154:155], v[154:155], v[232:233]
	v_pk_fma_f32 v[230:231], v[144:145], v[144:145], v[230:231]
	v_pk_fma_f32 v[232:233], v[146:147], v[146:147], v[232:233]
	v_pk_fma_f32 v[230:231], v[136:137], v[136:137], v[230:231]
	v_pk_fma_f32 v[232:233], v[138:139], v[138:139], v[232:233]
	v_pk_add_f32 v[230:231], v[230:231], v[232:233]
	v_add_f32_e32 v214, v230, v231
	s_waitcnt vmcnt(14)
	v_lshlrev_b32_e32 v230, 16, v184
	v_and_b32_e32 v231, s28, v184
	v_lshlrev_b32_e32 v232, 16, v185
	v_and_b32_e32 v233, s28, v185
	v_lshlrev_b32_e32 v234, 16, v186
	v_and_b32_e32 v235, s28, v186
	v_lshlrev_b32_e32 v236, 16, v187
	v_and_b32_e32 v237, s28, v187
	v_pk_add_f32 v[120:121], v[120:121], v[230:231]
	v_pk_add_f32 v[122:123], v[122:123], v[232:233]
	v_pk_add_f32 v[116:117], v[116:117], v[234:235]
	v_pk_add_f32 v[118:119], v[118:119], v[236:237]
	v_cvt_pk_bf16_f32 v184, v120, v121
	v_cvt_pk_bf16_f32 v185, v122, v123
	v_cvt_pk_bf16_f32 v186, v116, v117
	v_cvt_pk_bf16_f32 v187, v118, v119
	global_store_dwordx4 v[216:217], v[184:187], off
	v_lshlrev_b32_e32 v230, 16, v180
	v_and_b32_e32 v231, s28, v180
	v_lshlrev_b32_e32 v232, 16, v181
	v_and_b32_e32 v233, s28, v181
	v_lshlrev_b32_e32 v234, 16, v182
	v_and_b32_e32 v235, s28, v182
	v_lshlrev_b32_e32 v236, 16, v183
	v_and_b32_e32 v237, s28, v183
	v_pk_add_f32 v[104:105], v[104:105], v[230:231]
	v_pk_add_f32 v[106:107], v[106:107], v[232:233]
	v_pk_add_f32 v[100:101], v[100:101], v[234:235]
	v_pk_add_f32 v[102:103], v[102:103], v[236:237]
	v_cvt_pk_bf16_f32 v180, v104, v105
	v_cvt_pk_bf16_f32 v181, v106, v107
	v_cvt_pk_bf16_f32 v182, v100, v101
	v_cvt_pk_bf16_f32 v183, v102, v103
	global_store_dwordx4 v[216:217], v[180:183], off offset:256
	v_pk_mul_f32 v[230:231], v[120:121], v[120:121]
	v_pk_mul_f32 v[232:233], v[122:123], v[122:123]
	v_pk_fma_f32 v[230:231], v[116:117], v[116:117], v[230:231]
	v_pk_fma_f32 v[232:233], v[118:119], v[118:119], v[232:233]
	v_pk_fma_f32 v[230:231], v[104:105], v[104:105], v[230:231]
	v_pk_fma_f32 v[232:233], v[106:107], v[106:107], v[232:233]
	v_pk_fma_f32 v[230:231], v[100:101], v[100:101], v[230:231]
	v_pk_fma_f32 v[232:233], v[102:103], v[102:103], v[232:233]
	v_pk_add_f32 v[230:231], v[230:231], v[232:233]
	v_add_f32_e32 v216, v230, v231
	s_waitcnt vmcnt(14)
; __device__ __forceinline__ unsigned cvtpk(float lo, float hi) { f32x2 v = {lo, hi}; bf16x2_t b = __builtin_convertvector(v, bf16x2_t); return __builtin_bit_cast(unsigned, b); }
;     __device__ __forceinline__ void operator()(const f32x4 (&acc)[2][2][4][2], const Unit& u, int wr, int wc, int fr, int fq) const {
;     ...
;                 for (int bj = 0; bj < 2; ++bj) {
;                     const u32x4 wv = w[ai][m][bj];
;                     f32x4 o0 = acc[ai][bj][m][0], o1 = acc[ai][bj][m][1];
;                     o0[0] += __builtin_bit_cast(float, wv.x << 16); o0[1] += __builtin_bit_cast(float, wv.x & 0xffff0000u); o0[2] += __builtin_bit_cast(float, wv.y << 16); o0[3] += __builtin_bit_cast(float, wv.y & 0xffff0000u);
;                     o1[0] += __builtin_bit_cast(float, wv.z << 16); o1[1] += __builtin_bit_cast(float, wv.z & 0xffff0000u); o1[2] += __builtin_bit_cast(float, wv.w << 16); o1[3] += __builtin_bit_cast(float, wv.w & 0xffff0000u);
;                     if (last) { *(f32x4*)(out + off + bj * HALF) = o0; *(f32x4*)(out + off + bj * HALF + 4) = o1; }
;                     else {
;                         u32x4 v; v.x = cvtpk(o0[0], o0[1]); v.y = cvtpk(o0[2], o0[3]); v.z = cvtpk(o1[0], o1[1]); v.w = cvtpk(o1[2], o1[3]);
;                         *(u32x4*)(xb + off + bj * HALF) = v;
;                         ss += (o0[0] * o0[0] + o0[1] * o0[1]) + (o0[2] * o0[2] + o0[3] * o0[3]) + (o1[0] * o1[0] + o1[1] * o1[1]) + (o1[2] * o1[2] + o1[3] * o1[3]);
	v_lshlrev_b32_e32 v230, 16, v176
	v_and_b32_e32 v231, s28, v176
	v_lshlrev_b32_e32 v232, 16, v177
	v_and_b32_e32 v233, s28, v177
	v_lshlrev_b32_e32 v234, 16, v178
	v_and_b32_e32 v235, s28, v178
	v_lshlrev_b32_e32 v236, 16, v179
	v_and_b32_e32 v237, s28, v179
	v_pk_add_f32 v[96:97], v[96:97], v[230:231]
	v_pk_add_f32 v[98:99], v[98:99], v[232:233]
	v_pk_add_f32 v[92:93], v[92:93], v[234:235]
	v_pk_add_f32 v[94:95], v[94:95], v[236:237]
	v_cvt_pk_bf16_f32 v176, v96, v97
	v_cvt_pk_bf16_f32 v177, v98, v99
	v_cvt_pk_bf16_f32 v178, v92, v93
	v_cvt_pk_bf16_f32 v179, v94, v95
	global_store_dwordx4 v[218:219], v[176:179], off
	v_lshlrev_b32_e32 v230, 16, v172
	v_and_b32_e32 v231, s28, v172
	v_lshlrev_b32_e32 v232, 16, v173
	v_and_b32_e32 v233, s28, v173
	v_lshlrev_b32_e32 v234, 16, v174
	v_and_b32_e32 v235, s28, v174
	v_lshlrev_b32_e32 v236, 16, v175
	v_and_b32_e32 v237, s28, v175
	v_pk_add_f32 v[88:89], v[88:89], v[230:231]
	v_pk_add_f32 v[90:91], v[90:91], v[232:233]
	v_pk_add_f32 v[84:85], v[84:85], v[234:235]
	v_pk_add_f32 v[86:87], v[86:87], v[236:237]
	v_cvt_pk_bf16_f32 v172, v88, v89
	v_cvt_pk_bf16_f32 v173, v90, v91
	v_cvt_pk_bf16_f32 v174, v84, v85
	v_cvt_pk_bf16_f32 v175, v86, v87
	global_store_dwordx4 v[218:219], v[172:175], off offset:256
	v_pk_mul_f32 v[230:231], v[96:97], v[96:97]
	v_pk_mul_f32 v[232:233], v[98:99], v[98:99]
	v_pk_fma_f32 v[230:231], v[92:93], v[92:93], v[230:231]
	v_pk_fma_f32 v[232:233], v[94:95], v[94:95], v[232:233]
	v_pk_fma_f32 v[230:231], v[88:89], v[88:89], v[230:231]
	v_pk_fma_f32 v[232:233], v[90:91], v[90:91], v[232:233]
	v_pk_fma_f32 v[230:231], v[84:85], v[84:85], v[230:231]
	v_pk_fma_f32 v[232:233], v[86:87], v[86:87], v[232:233]
	v_pk_add_f32 v[230:231], v[230:231], v[232:233]
	v_add_f32_e32 v218, v230, v231
	s_waitcnt vmcnt(14)
	v_lshlrev_b32_e32 v230, 16, v168
	v_and_b32_e32 v231, s28, v168
	v_lshlrev_b32_e32 v232, 16, v169
	v_and_b32_e32 v233, s28, v169
	v_lshlrev_b32_e32 v234, 16, v170
	v_and_b32_e32 v235, s28, v170
	v_lshlrev_b32_e32 v236, 16, v171
	v_and_b32_e32 v237, s28, v171
	v_pk_add_f32 v[80:81], v[80:81], v[230:231]
	v_pk_add_f32 v[82:83], v[82:83], v[232:233]
	v_pk_add_f32 v[76:77], v[76:77], v[234:235]
	v_pk_add_f32 v[78:79], v[78:79], v[236:237]
	v_cvt_pk_bf16_f32 v168, v80, v81
	v_cvt_pk_bf16_f32 v169, v82, v83
	v_cvt_pk_bf16_f32 v170, v76, v77
	v_cvt_pk_bf16_f32 v171, v78, v79
	global_store_dwordx4 v[220:221], v[168:171], off
	v_lshlrev_b32_e32 v230, 16, v164
	v_and_b32_e32 v231, s28, v164
	v_lshlrev_b32_e32 v232, 16, v165
	v_and_b32_e32 v233, s28, v165
	v_lshlrev_b32_e32 v234, 16, v166
	v_and_b32_e32 v235, s28, v166
	v_lshlrev_b32_e32 v236, 16, v167
	v_and_b32_e32 v237, s28, v167
	v_pk_add_f32 v[72:73], v[72:73], v[230:231]
	v_pk_add_f32 v[74:75], v[74:75], v[232:233]
	v_pk_add_f32 v[68:69], v[68:69], v[234:235]
	v_pk_add_f32 v[70:71], v[70:71], v[236:237]
	v_cvt_pk_bf16_f32 v164, v72, v73
	v_cvt_pk_bf16_f32 v165, v74, v75
	v_cvt_pk_bf16_f32 v166, v68, v69
	v_cvt_pk_bf16_f32 v167, v70, v71
	global_store_dwordx4 v[220:221], v[164:167], off offset:256
	v_pk_mul_f32 v[230:231], v[80:81], v[80:81]
	v_pk_mul_f32 v[232:233], v[82:83], v[82:83]
	v_pk_fma_f32 v[230:231], v[76:77], v[76:77], v[230:231]
	v_pk_fma_f32 v[232:233], v[78:79], v[78:79], v[232:233]
	v_pk_fma_f32 v[230:231], v[72:73], v[72:73], v[230:231]
	v_pk_fma_f32 v[232:233], v[74:75], v[74:75], v[232:233]
	v_pk_fma_f32 v[230:231], v[68:69], v[68:69], v[230:231]
	v_pk_fma_f32 v[232:233], v[70:71], v[70:71], v[232:233]
	v_pk_add_f32 v[230:231], v[230:231], v[232:233]
	v_add_f32_e32 v220, v230, v231
	s_waitcnt vmcnt(14)
	v_lshlrev_b32_e32 v230, 16, v156
	v_and_b32_e32 v231, s28, v156
	v_lshlrev_b32_e32 v232, 16, v157
	v_and_b32_e32 v233, s28, v157
	v_lshlrev_b32_e32 v234, 16, v158
	v_and_b32_e32 v235, s28, v158
	v_lshlrev_b32_e32 v236, 16, v159
	v_and_b32_e32 v237, s28, v159
	v_pk_add_f32 v[64:65], v[64:65], v[230:231]
	v_pk_add_f32 v[66:67], v[66:67], v[232:233]
	v_pk_add_f32 v[60:61], v[60:61], v[234:235]
	v_pk_add_f32 v[62:63], v[62:63], v[236:237]
	v_cvt_pk_bf16_f32 v156, v64, v65
	v_cvt_pk_bf16_f32 v157, v66, v67
	v_cvt_pk_bf16_f32 v158, v60, v61
	v_cvt_pk_bf16_f32 v159, v62, v63
	global_store_dwordx4 v[222:223], v[156:159], off
	v_lshlrev_b32_e32 v230, 16, v148
	v_and_b32_e32 v231, s28, v148
	v_lshlrev_b32_e32 v232, 16, v149
	v_and_b32_e32 v233, s28, v149
	v_lshlrev_b32_e32 v234, 16, v150
	v_and_b32_e32 v235, s28, v150
	v_lshlrev_b32_e32 v236, 16, v151
	v_and_b32_e32 v237, s28, v151
	v_pk_add_f32 v[56:57], v[56:57], v[230:231]
	v_pk_add_f32 v[58:59], v[58:59], v[232:233]
	v_pk_add_f32 v[52:53], v[52:53], v[234:235]
	v_pk_add_f32 v[54:55], v[54:55], v[236:237]
	v_cvt_pk_bf16_f32 v148, v56, v57
	v_cvt_pk_bf16_f32 v149, v58, v59
	v_cvt_pk_bf16_f32 v150, v52, v53
	v_cvt_pk_bf16_f32 v151, v54, v55
	global_store_dwordx4 v[222:223], v[148:151], off offset:256
	v_pk_mul_f32 v[230:231], v[64:65], v[64:65]
	v_pk_mul_f32 v[232:233], v[66:67], v[66:67]
	v_pk_fma_f32 v[230:231], v[60:61], v[60:61], v[230:231]
	v_pk_fma_f32 v[232:233], v[62:63], v[62:63], v[232:233]
	v_pk_fma_f32 v[230:231], v[56:57], v[56:57], v[230:231]
	v_pk_fma_f32 v[232:233], v[58:59], v[58:59], v[232:233]
	v_pk_fma_f32 v[230:231], v[52:53], v[52:53], v[230:231]
	v_pk_fma_f32 v[232:233], v[54:55], v[54:55], v[232:233]
	v_pk_add_f32 v[230:231], v[230:231], v[232:233]
	v_add_f32_e32 v222, v230, v231
	s_waitcnt vmcnt(14)
; __device__ __forceinline__ unsigned cvtpk(float lo, float hi) { f32x2 v = {lo, hi}; bf16x2_t b = __builtin_convertvector(v, bf16x2_t); return __builtin_bit_cast(unsigned, b); }
;     __device__ __forceinline__ void operator()(const f32x4 (&acc)[2][2][4][2], const Unit& u, int wr, int wc, int fr, int fq) const {
;     ...
;                 for (int bj = 0; bj < 2; ++bj) {
;                     const u32x4 wv = w[ai][m][bj];
;                     f32x4 o0 = acc[ai][bj][m][0], o1 = acc[ai][bj][m][1];
;                     o0[0] += __builtin_bit_cast(float, wv.x << 16); o0[1] += __builtin_bit_cast(float, wv.x & 0xffff0000u); o0[2] += __builtin_bit_cast(float, wv.y << 16); o0[3] += __builtin_bit_cast(float, wv.y & 0xffff0000u);
;                     o1[0] += __builtin_bit_cast(float, wv.z << 16); o1[1] += __builtin_bit_cast(float, wv.z & 0xffff0000u); o1[2] += __builtin_bit_cast(float, wv.w << 16); o1[3] += __builtin_bit_cast(float, wv.w & 0xffff0000u);
;                     if (last) { *(f32x4*)(out + off + bj * HALF) = o0; *(f32x4*)(out + off + bj * HALF + 4) = o1; }
;                     else {
;                         u32x4 v; v.x = cvtpk(o0[0], o0[1]); v.y = cvtpk(o0[2], o0[3]); v.z = cvtpk(o1[0], o1[1]); v.w = cvtpk(o1[2], o1[3]);
;                         *(u32x4*)(xb + off + bj * HALF) = v;
;                         ss += (o0[0] * o0[0] + o0[1] * o0[1]) + (o0[2] * o0[2] + o0[3] * o0[3]) + (o1[0] * o1[0] + o1[1] * o1[1]) + (o1[2] * o1[2] + o1[3] * o1[3]);
;                     }
;                 }
;                 if (!last) {
;                     ss += __shfl_xor(ss, 16); ss += __shfl_xor(ss, 32);
;                     if (fq == 0) ssq_out[(size_t)row * 16 + 4 * u.pn + wc] = ss;
;                 }
	v_lshlrev_b32_e32 v230, 16, v140
	v_and_b32_e32 v231, s28, v140
	v_lshlrev_b32_e32 v232, 16, v141
	v_and_b32_e32 v233, s28, v141
	v_lshlrev_b32_e32 v234, 16, v142
	v_and_b32_e32 v235, s28, v142
	v_lshlrev_b32_e32 v236, 16, v143
	v_and_b32_e32 v237, s28, v143
	v_pk_add_f32 v[48:49], v[48:49], v[230:231]
	v_pk_add_f32 v[50:51], v[50:51], v[232:233]
	v_pk_add_f32 v[44:45], v[44:45], v[234:235]
	v_pk_add_f32 v[46:47], v[46:47], v[236:237]
	v_cvt_pk_bf16_f32 v140, v48, v49
	v_cvt_pk_bf16_f32 v141, v50, v51
	v_cvt_pk_bf16_f32 v142, v44, v45
	v_cvt_pk_bf16_f32 v143, v46, v47
	global_store_dwordx4 v[224:225], v[140:143], off
	v_lshlrev_b32_e32 v230, 16, v132
	v_and_b32_e32 v231, s28, v132
	v_lshlrev_b32_e32 v232, 16, v133
	v_and_b32_e32 v233, s28, v133
	v_lshlrev_b32_e32 v234, 16, v134
	v_and_b32_e32 v235, s28, v134
	v_lshlrev_b32_e32 v236, 16, v135
	v_and_b32_e32 v237, s28, v135
	v_pk_add_f32 v[40:41], v[40:41], v[230:231]
	v_pk_add_f32 v[42:43], v[42:43], v[232:233]
	v_pk_add_f32 v[36:37], v[36:37], v[234:235]
	v_pk_add_f32 v[38:39], v[38:39], v[236:237]
	v_cvt_pk_bf16_f32 v132, v40, v41
	v_cvt_pk_bf16_f32 v133, v42, v43
	v_cvt_pk_bf16_f32 v134, v36, v37
	v_cvt_pk_bf16_f32 v135, v38, v39
	global_store_dwordx4 v[224:225], v[132:135], off offset:256
	v_pk_mul_f32 v[230:231], v[48:49], v[48:49]
	v_pk_mul_f32 v[232:233], v[50:51], v[50:51]
	v_pk_fma_f32 v[230:231], v[44:45], v[44:45], v[230:231]
	v_pk_fma_f32 v[232:233], v[46:47], v[46:47], v[232:233]
	v_pk_fma_f32 v[230:231], v[40:41], v[40:41], v[230:231]
	v_pk_fma_f32 v[232:233], v[42:43], v[42:43], v[232:233]
	v_pk_fma_f32 v[230:231], v[36:37], v[36:37], v[230:231]
	v_pk_fma_f32 v[232:233], v[38:39], v[38:39], v[232:233]
	v_pk_add_f32 v[230:231], v[230:231], v[232:233]
	v_add_f32_e32 v224, v230, v231
	s_waitcnt vmcnt(14)
	v_lshlrev_b32_e32 v230, 16, v128
	v_and_b32_e32 v231, s28, v128
	v_lshlrev_b32_e32 v232, 16, v129
	v_and_b32_e32 v233, s28, v129
	v_lshlrev_b32_e32 v234, 16, v130
	v_and_b32_e32 v235, s28, v130
	v_lshlrev_b32_e32 v236, 16, v131
	v_and_b32_e32 v237, s28, v131
	v_pk_add_f32 v[32:33], v[32:33], v[230:231]
	v_pk_add_f32 v[34:35], v[34:35], v[232:233]
	v_pk_add_f32 v[28:29], v[28:29], v[234:235]
	v_pk_add_f32 v[30:31], v[30:31], v[236:237]
	v_cvt_pk_bf16_f32 v128, v32, v33
	v_cvt_pk_bf16_f32 v129, v34, v35
	v_cvt_pk_bf16_f32 v130, v28, v29
	v_cvt_pk_bf16_f32 v131, v30, v31
	global_store_dwordx4 v[226:227], v[128:131], off
	v_lshlrev_b32_e32 v230, 16, v112
	v_and_b32_e32 v231, s28, v112
	v_lshlrev_b32_e32 v232, 16, v113
	v_and_b32_e32 v233, s28, v113
	v_lshlrev_b32_e32 v234, 16, v114
	v_and_b32_e32 v235, s28, v114
	v_lshlrev_b32_e32 v236, 16, v115
	v_and_b32_e32 v237, s28, v115
	v_pk_add_f32 v[24:25], v[24:25], v[230:231]
	v_pk_add_f32 v[26:27], v[26:27], v[232:233]
	v_pk_add_f32 v[20:21], v[20:21], v[234:235]
	v_pk_add_f32 v[22:23], v[22:23], v[236:237]
	v_cvt_pk_bf16_f32 v112, v24, v25
	v_cvt_pk_bf16_f32 v113, v26, v27
	v_cvt_pk_bf16_f32 v114, v20, v21
	v_cvt_pk_bf16_f32 v115, v22, v23
	global_store_dwordx4 v[226:227], v[112:115], off offset:256
	v_pk_mul_f32 v[230:231], v[32:33], v[32:33]
	v_pk_mul_f32 v[232:233], v[34:35], v[34:35]
	v_pk_fma_f32 v[230:231], v[28:29], v[28:29], v[230:231]
	v_pk_fma_f32 v[232:233], v[30:31], v[30:31], v[232:233]
	v_pk_fma_f32 v[230:231], v[24:25], v[24:25], v[230:231]
	v_pk_fma_f32 v[232:233], v[26:27], v[26:27], v[232:233]
	v_pk_fma_f32 v[230:231], v[20:21], v[20:21], v[230:231]
	v_pk_fma_f32 v[232:233], v[22:23], v[22:23], v[232:233]
	v_pk_add_f32 v[230:231], v[230:231], v[232:233]
	v_add_f32_e32 v226, v230, v231
	s_waitcnt vmcnt(14)
	v_lshlrev_b32_e32 v230, 16, v124
	v_and_b32_e32 v231, s28, v124
	v_lshlrev_b32_e32 v232, 16, v125
	v_and_b32_e32 v233, s28, v125
	v_lshlrev_b32_e32 v234, 16, v126
	v_and_b32_e32 v235, s28, v126
	v_lshlrev_b32_e32 v236, 16, v127
	v_and_b32_e32 v237, s28, v127
	v_pk_add_f32 v[16:17], v[16:17], v[230:231]
	v_pk_add_f32 v[18:19], v[18:19], v[232:233]
	v_pk_add_f32 v[12:13], v[12:13], v[234:235]
	v_pk_add_f32 v[14:15], v[14:15], v[236:237]
	v_cvt_pk_bf16_f32 v124, v16, v17
	v_cvt_pk_bf16_f32 v125, v18, v19
	v_cvt_pk_bf16_f32 v126, v12, v13
	v_cvt_pk_bf16_f32 v127, v14, v15
	global_store_dwordx4 v[228:229], v[124:127], off
	v_lshlrev_b32_e32 v230, 16, v108
	v_and_b32_e32 v231, s28, v108
	v_lshlrev_b32_e32 v232, 16, v109
	v_and_b32_e32 v233, s28, v109
	v_lshlrev_b32_e32 v234, 16, v110
	v_and_b32_e32 v235, s28, v110
	v_lshlrev_b32_e32 v236, 16, v111
	v_and_b32_e32 v237, s28, v111
	v_pk_add_f32 v[8:9], v[8:9], v[230:231]
	v_pk_add_f32 v[10:11], v[10:11], v[232:233]
	v_pk_add_f32 v[4:5], v[4:5], v[234:235]
	v_pk_add_f32 v[6:7], v[6:7], v[236:237]
	v_cvt_pk_bf16_f32 v108, v8, v9
	v_cvt_pk_bf16_f32 v109, v10, v11
	v_cvt_pk_bf16_f32 v110, v4, v5
	v_cvt_pk_bf16_f32 v111, v6, v7
	global_store_dwordx4 v[228:229], v[108:111], off offset:256
	v_pk_mul_f32 v[230:231], v[16:17], v[16:17]
	v_pk_mul_f32 v[232:233], v[18:19], v[18:19]
	v_pk_fma_f32 v[230:231], v[12:13], v[12:13], v[230:231]
	v_pk_fma_f32 v[232:233], v[14:15], v[14:15], v[232:233]
	v_pk_fma_f32 v[230:231], v[8:9], v[8:9], v[230:231]
	v_pk_fma_f32 v[232:233], v[10:11], v[10:11], v[232:233]
	v_pk_fma_f32 v[230:231], v[4:5], v[4:5], v[230:231]
	v_pk_fma_f32 v[232:233], v[6:7], v[6:7], v[232:233]
	v_pk_add_f32 v[230:231], v[230:231], v[232:233]
	v_add_f32_e32 v228, v230, v231
	s_nop 1
	v_permlane32_swap_b32_e32 v214, v216
	v_permlane32_swap_b32_e32 v218, v220
	v_permlane32_swap_b32_e32 v222, v224
	v_permlane32_swap_b32_e32 v226, v228
	v_add_f32_e32 v214, v214, v216
	v_add_f32_e32 v218, v218, v220
	v_add_f32_e32 v222, v222, v224
	v_add_f32_e32 v226, v226, v228
	s_nop 1
	v_permlane16_swap_b32_e32 v214, v218
	v_permlane16_swap_b32_e32 v222, v226
	v_add_f32_e32 v214, v214, v218
	v_add_f32_e32 v222, v222, v226
	v_bfe_u32 v230, v250, 4, 1
	v_bfe_u32 v231, v250, 5, 1
	v_lshl_or_b32 v230, v230, 1, v231
	v_lshlrev_b32_e32 v232, 6, v212
	v_lshl_add_u32 v232, v230, 10, v232
	s_lshl_b32 s29, s24, 4
	s_lshl_b32 s27, s48, 2
	s_add_i32 s29, s29, s27
	v_add_u32_e32 v232, s29, v232
	v_mov_b32_e32 v233, v2
	v_lshl_add_u64 v[232:233], s[12:13], 0, v[232:233]
	s_mov_b32 s100, 0x2000
	v_lshl_add_u64 v[234:235], v[232:233], 0, s[100:101]
	global_store_dword v[232:233], v214, off
	global_store_dword v[234:235], v222, off
	s_andn2_b64 vcc, exec, s[6:7]
	s_mov_b64 s[6:7], -1
	s_cbranch_vccnz .LBB0_321
	s_andn2_b64 vcc, exec, s[8:9]
	s_cbranch_vccnz .LBB0_320
	s_barrier
	s_branch .LBB0_320

; __device__ __forceinline__ unsigned cvtpk(float lo, float hi) { f32x2 v = {lo, hi}; bf16x2_t b = __builtin_convertvector(v, bf16x2_t); return __builtin_bit_cast(unsigned, b); }
;     __device__ __forceinline__ void operator()(const f32x4 (&acc)[2][2][4][2], const Unit& u, int wr, int wc, int fr, int fq) const {
;         const int row0 = u.pm * BM + wr * 64 + fr;
;         const int col0 = u.pn * BM + wc * 32 + 8 * fq;
;         u32x4 w[2][4][2];
; #pragma unroll
;         for (int ai = 0; ai < 2; ++ai)
; #pragma unroll
;             for (int m = 0; m < 4; ++m)
; #pragma unroll
;                 for (int bj = 0; bj < 2; ++bj) w[ai][m][bj] = *(const u32x4*)(xb + (size_t)(row0 + ai * HALF + m * 16) * 1024 + col0 + bj * HALF);
; #pragma unroll
;         for (int ai = 0; ai < 2; ++ai)
; #pragma unroll
;             for (int m = 0; m < 4; ++m) {
;                 const int row = row0 + ai * HALF + m * 16;
;                 const size_t off = (size_t)row * 1024 + col0;
;                 float ss = 0.f;
; #pragma unroll
;                 for (int bj = 0; bj < 2; ++bj) {
;                     const u32x4 wv = w[ai][m][bj];
;                     f32x4 o0 = acc[ai][bj][m][0], o1 = acc[ai][bj][m][1];
;                     o0[0] += __builtin_bit_cast(float, wv.x << 16); o0[1] += __builtin_bit_cast(float, wv.x & 0xffff0000u); o0[2] += __builtin_bit_cast(float, wv.y << 16); o0[3] += __builtin_bit_cast(float, wv.y & 0xffff0000u);
;                     o1[0] += __builtin_bit_cast(float, wv.z << 16); o1[1] += __builtin_bit_cast(float, wv.z & 0xffff0000u); o1[2] += __builtin_bit_cast(float, wv.w << 16); o1[3] += __builtin_bit_cast(float, wv.w & 0xffff0000u);
;                     if (last) { *(f32x4*)(out + off + bj * HALF) = o0; *(f32x4*)(out + off + bj * HALF + 4) = o1; }
;                     else {
;                         u32x4 v; v.x = cvtpk(o0[0], o0[1]); v.y = cvtpk(o0[2], o0[3]); v.z = cvtpk(o1[0], o1[1]); v.w = cvtpk(o1[2], o1[3]);
;                         *(u32x4*)(xb + off + bj * HALF) = v;
;                         ss += (o0[0] * o0[0] + o0[1] * o0[1]) + (o0[2] * o0[2] + o0[3] * o0[3]) + (o1[0] * o1[0] + o1[1] * o1[1]) + (o1[2] * o1[2] + o1[3] * o1[3]);
.LBB0_483:
	s_and_b64 vcc, exec, s[10:11]
	s_cbranch_vccz .Lrd_last
	v_lshl_add_u32 v208, s3, 8, v3
	v_lshl_or_b32 v209, s52, 8, v235
	v_lshlrev_b32_e32 v238, 1, v209
	v_lshl_add_u32 v238, v208, 11, v238
	v_mov_b32_e32 v239, v2
	s_mov_b32 s101, 0
	s_mov_b32 s28, 0xffff0000
	v_lshl_add_u64 v[210:211], s[18:19], 0, v[238:239]
	global_load_dwordx4 v[230:233], v[210:211], off
	global_load_dwordx4 v[188:191], v[210:211], off offset:256
	s_mov_b32 s100, 0x8000
	v_lshl_add_u64 v[212:213], v[210:211], 0, s[100:101]
	global_load_dwordx4 v[184:187], v[212:213], off
	global_load_dwordx4 v[180:183], v[212:213], off offset:256
	s_mov_b32 s100, 0x10000
	v_lshl_add_u64 v[214:215], v[210:211], 0, s[100:101]
	global_load_dwordx4 v[176:179], v[214:215], off
	global_load_dwordx4 v[172:175], v[214:215], off offset:256
	s_mov_b32 s100, 0x18000
	v_lshl_add_u64 v[216:217], v[210:211], 0, s[100:101]
	global_load_dwordx4 v[168:171], v[216:217], off
	global_load_dwordx4 v[156:159], v[216:217], off offset:256
	s_mov_b32 s100, 0x40000
	v_lshl_add_u64 v[218:219], v[210:211], 0, s[100:101]
	global_load_dwordx4 v[144:147], v[218:219], off
	global_load_dwordx4 v[132:135], v[218:219], off offset:256
	s_mov_b32 s100, 0x48000
	v_lshl_add_u64 v[220:221], v[210:211], 0, s[100:101]
	global_load_dwordx4 v[120:123], v[220:221], off
	global_load_dwordx4 v[112:115], v[220:221], off offset:256
	s_mov_b32 s100, 0x50000
	v_lshl_add_u64 v[222:223], v[210:211], 0, s[100:101]
	global_load_dwordx4 v[100:103], v[222:223], off
	global_load_dwordx4 v[92:95], v[222:223], off offset:256
	s_mov_b32 s100, 0x58000
	v_lshl_add_u64 v[224:225], v[210:211], 0, s[100:101]
	global_load_dwordx4 v[80:83], v[224:225], off
	global_load_dwordx4 v[68:71], v[224:225], off offset:256
	s_waitcnt vmcnt(14)
	v_lshlrev_b32_e32 v238, 16, v230
	v_and_b32_e32 v239, s28, v230
	v_lshlrev_b32_e32 v240, 16, v231
	v_and_b32_e32 v241, s28, v231
	v_lshlrev_b32_e32 v242, 16, v232
	v_and_b32_e32 v243, s28, v232
	v_lshlrev_b32_e32 v198, 16, v233
	v_and_b32_e32 v199, s28, v233
	v_pk_add_f32 v[164:165], v[164:165], v[238:239]
	v_pk_add_f32 v[166:167], v[166:167], v[240:241]
	v_pk_add_f32 v[160:161], v[160:161], v[242:243]
	v_pk_add_f32 v[162:163], v[162:163], v[198:199]
	v_cvt_pk_bf16_f32 v230, v164, v165
	v_cvt_pk_bf16_f32 v231, v166, v167
	v_cvt_pk_bf16_f32 v232, v160, v161
	v_cvt_pk_bf16_f32 v233, v162, v163
	global_store_dwordx4 v[210:211], v[230:233], off
	v_lshlrev_b32_e32 v238, 16, v188
	v_and_b32_e32 v239, s28, v188
	v_lshlrev_b32_e32 v240, 16, v189
	v_and_b32_e32 v241, s28, v189
	v_lshlrev_b32_e32 v242, 16, v190
	v_and_b32_e32 v243, s28, v190
	v_lshlrev_b32_e32 v198, 16, v191
	v_and_b32_e32 v199, s28, v191
	v_pk_add_f32 v[152:153], v[152:153], v[238:239]
	v_pk_add_f32 v[154:155], v[154:155], v[240:241]
	v_pk_add_f32 v[148:149], v[148:149], v[242:243]
	v_pk_add_f32 v[150:151], v[150:151], v[198:199]
	v_cvt_pk_bf16_f32 v188, v152, v153
	v_cvt_pk_bf16_f32 v189, v154, v155
	v_cvt_pk_bf16_f32 v190, v148, v149
	v_cvt_pk_bf16_f32 v191, v150, v151
	global_store_dwordx4 v[210:211], v[188:191], off offset:256
	v_pk_mul_f32 v[238:239], v[164:165], v[164:165]
	v_pk_mul_f32 v[240:241], v[166:167], v[166:167]
	v_pk_fma_f32 v[238:239], v[160:161], v[160:161], v[238:239]
	v_pk_fma_f32 v[240:241], v[162:163], v[162:163], v[240:241]
	v_pk_fma_f32 v[238:239], v[152:153], v[152:153], v[238:239]
	v_pk_fma_f32 v[240:241], v[154:155], v[154:155], v[240:241]
	v_pk_fma_f32 v[238:239], v[148:149], v[148:149], v[238:239]
	v_pk_fma_f32 v[240:241], v[150:151], v[150:151], v[240:241]
	v_pk_add_f32 v[238:239], v[238:239], v[240:241]
	v_add_f32_e32 v210, v238, v239
	s_waitcnt vmcnt(14)
	v_lshlrev_b32_e32 v238, 16, v184
	v_and_b32_e32 v239, s28, v184
	v_lshlrev_b32_e32 v240, 16, v185
	v_and_b32_e32 v241, s28, v185
	v_lshlrev_b32_e32 v242, 16, v186
	v_and_b32_e32 v243, s28, v186
	v_lshlrev_b32_e32 v198, 16, v187
	v_and_b32_e32 v199, s28, v187
	v_pk_add_f32 v[140:141], v[140:141], v[238:239]
	v_pk_add_f32 v[142:143], v[142:143], v[240:241]
	v_pk_add_f32 v[136:137], v[136:137], v[242:243]
	v_pk_add_f32 v[138:139], v[138:139], v[198:199]
	v_cvt_pk_bf16_f32 v184, v140, v141
	v_cvt_pk_bf16_f32 v185, v142, v143
	v_cvt_pk_bf16_f32 v186, v136, v137
	v_cvt_pk_bf16_f32 v187, v138, v139
	global_store_dwordx4 v[212:213], v[184:187], off
	v_lshlrev_b32_e32 v238, 16, v180
	v_and_b32_e32 v239, s28, v180
	v_lshlrev_b32_e32 v240, 16, v181
	v_and_b32_e32 v241, s28, v181
	v_lshlrev_b32_e32 v242, 16, v182
	v_and_b32_e32 v243, s28, v182
	v_lshlrev_b32_e32 v198, 16, v183
	v_and_b32_e32 v199, s28, v183
	v_pk_add_f32 v[128:129], v[128:129], v[238:239]
	v_pk_add_f32 v[130:131], v[130:131], v[240:241]
	v_pk_add_f32 v[124:125], v[124:125], v[242:243]
	v_pk_add_f32 v[126:127], v[126:127], v[198:199]
	v_cvt_pk_bf16_f32 v180, v128, v129
	v_cvt_pk_bf16_f32 v181, v130, v131
	v_cvt_pk_bf16_f32 v182, v124, v125
	v_cvt_pk_bf16_f32 v183, v126, v127
	global_store_dwordx4 v[212:213], v[180:183], off offset:256
	v_pk_mul_f32 v[238:239], v[140:141], v[140:141]
	v_pk_mul_f32 v[240:241], v[142:143], v[142:143]
	v_pk_fma_f32 v[238:239], v[136:137], v[136:137], v[238:239]
	v_pk_fma_f32 v[240:241], v[138:139], v[138:139], v[240:241]
	v_pk_fma_f32 v[238:239], v[128:129], v[128:129], v[238:239]
	v_pk_fma_f32 v[240:241], v[130:131], v[130:131], v[240:241]
	v_pk_fma_f32 v[238:239], v[124:125], v[124:125], v[238:239]
	v_pk_fma_f32 v[240:241], v[126:127], v[126:127], v[240:241]
	v_pk_add_f32 v[238:239], v[238:239], v[240:241]
	v_add_f32_e32 v212, v238, v239
	s_waitcnt vmcnt(14)
; __device__ __forceinline__ unsigned cvtpk(float lo, float hi) { f32x2 v = {lo, hi}; bf16x2_t b = __builtin_convertvector(v, bf16x2_t); return __builtin_bit_cast(unsigned, b); }
;     __device__ __forceinline__ void operator()(const f32x4 (&acc)[2][2][4][2], const Unit& u, int wr, int wc, int fr, int fq) const {
;     ...
;                 for (int bj = 0; bj < 2; ++bj) {
;                     const u32x4 wv = w[ai][m][bj];
;                     f32x4 o0 = acc[ai][bj][m][0], o1 = acc[ai][bj][m][1];
;                     o0[0] += __builtin_bit_cast(float, wv.x << 16); o0[1] += __builtin_bit_cast(float, wv.x & 0xffff0000u); o0[2] += __builtin_bit_cast(float, wv.y << 16); o0[3] += __builtin_bit_cast(float, wv.y & 0xffff0000u);
;                     o1[0] += __builtin_bit_cast(float, wv.z << 16); o1[1] += __builtin_bit_cast(float, wv.z & 0xffff0000u); o1[2] += __builtin_bit_cast(float, wv.w << 16); o1[3] += __builtin_bit_cast(float, wv.w & 0xffff0000u);
;                     if (last) { *(f32x4*)(out + off + bj * HALF) = o0; *(f32x4*)(out + off + bj * HALF + 4) = o1; }
;                     else {
;                         u32x4 v; v.x = cvtpk(o0[0], o0[1]); v.y = cvtpk(o0[2], o0[3]); v.z = cvtpk(o1[0], o1[1]); v.w = cvtpk(o1[2], o1[3]);
;                         *(u32x4*)(xb + off + bj * HALF) = v;
;                         ss += (o0[0] * o0[0] + o0[1] * o0[1]) + (o0[2] * o0[2] + o0[3] * o0[3]) + (o1[0] * o1[0] + o1[1] * o1[1]) + (o1[2] * o1[2] + o1[3] * o1[3]);
	v_lshlrev_b32_e32 v238, 16, v176
	v_and_b32_e32 v239, s28, v176
	v_lshlrev_b32_e32 v240, 16, v177
	v_and_b32_e32 v241, s28, v177
	v_lshlrev_b32_e32 v242, 16, v178
	v_and_b32_e32 v243, s28, v178
	v_lshlrev_b32_e32 v198, 16, v179
	v_and_b32_e32 v199, s28, v179
	v_pk_add_f32 v[116:117], v[116:117], v[238:239]
	v_pk_add_f32 v[118:119], v[118:119], v[240:241]
	v_pk_add_f32 v[108:109], v[108:109], v[242:243]
	v_pk_add_f32 v[110:111], v[110:111], v[198:199]
	v_cvt_pk_bf16_f32 v176, v116, v117
	v_cvt_pk_bf16_f32 v177, v118, v119
	v_cvt_pk_bf16_f32 v178, v108, v109
	v_cvt_pk_bf16_f32 v179, v110, v111
	global_store_dwordx4 v[214:215], v[176:179], off
	v_lshlrev_b32_e32 v238, 16, v172
	v_and_b32_e32 v239, s28, v172
	v_lshlrev_b32_e32 v240, 16, v173
	v_and_b32_e32 v241, s28, v173
	v_lshlrev_b32_e32 v242, 16, v174
	v_and_b32_e32 v243, s28, v174
	v_lshlrev_b32_e32 v198, 16, v175
	v_and_b32_e32 v199, s28, v175
	v_pk_add_f32 v[104:105], v[104:105], v[238:239]
	v_pk_add_f32 v[106:107], v[106:107], v[240:241]
	v_pk_add_f32 v[96:97], v[96:97], v[242:243]
	v_pk_add_f32 v[98:99], v[98:99], v[198:199]
	v_cvt_pk_bf16_f32 v172, v104, v105
	v_cvt_pk_bf16_f32 v173, v106, v107
	v_cvt_pk_bf16_f32 v174, v96, v97
	v_cvt_pk_bf16_f32 v175, v98, v99
	global_store_dwordx4 v[214:215], v[172:175], off offset:256
	v_pk_mul_f32 v[238:239], v[116:117], v[116:117]
	v_pk_mul_f32 v[240:241], v[118:119], v[118:119]
	v_pk_fma_f32 v[238:239], v[108:109], v[108:109], v[238:239]
	v_pk_fma_f32 v[240:241], v[110:111], v[110:111], v[240:241]
	v_pk_fma_f32 v[238:239], v[104:105], v[104:105], v[238:239]
	v_pk_fma_f32 v[240:241], v[106:107], v[106:107], v[240:241]
	v_pk_fma_f32 v[238:239], v[96:97], v[96:97], v[238:239]
	v_pk_fma_f32 v[240:241], v[98:99], v[98:99], v[240:241]
	v_pk_add_f32 v[238:239], v[238:239], v[240:241]
	v_add_f32_e32 v214, v238, v239
	s_waitcnt vmcnt(14)
	v_lshlrev_b32_e32 v238, 16, v168
	v_and_b32_e32 v239, s28, v168
	v_lshlrev_b32_e32 v240, 16, v169
	v_and_b32_e32 v241, s28, v169
	v_lshlrev_b32_e32 v242, 16, v170
	v_and_b32_e32 v243, s28, v170
	v_lshlrev_b32_e32 v198, 16, v171
	v_and_b32_e32 v199, s28, v171
	v_pk_add_f32 v[88:89], v[88:89], v[238:239]
	v_pk_add_f32 v[90:91], v[90:91], v[240:241]
	v_pk_add_f32 v[84:85], v[84:85], v[242:243]
	v_pk_add_f32 v[86:87], v[86:87], v[198:199]
	v_cvt_pk_bf16_f32 v168, v88, v89
	v_cvt_pk_bf16_f32 v169, v90, v91
	v_cvt_pk_bf16_f32 v170, v84, v85
	v_cvt_pk_bf16_f32 v171, v86, v87
	global_store_dwordx4 v[216:217], v[168:171], off
	v_lshlrev_b32_e32 v238, 16, v156
	v_and_b32_e32 v239, s28, v156
	v_lshlrev_b32_e32 v240, 16, v157
	v_and_b32_e32 v241, s28, v157
	v_lshlrev_b32_e32 v242, 16, v158
	v_and_b32_e32 v243, s28, v158
	v_lshlrev_b32_e32 v198, 16, v159
	v_and_b32_e32 v199, s28, v159
	v_pk_add_f32 v[76:77], v[76:77], v[238:239]
	v_pk_add_f32 v[78:79], v[78:79], v[240:241]
	v_pk_add_f32 v[72:73], v[72:73], v[242:243]
	v_pk_add_f32 v[74:75], v[74:75], v[198:199]
	v_cvt_pk_bf16_f32 v156, v76, v77
	v_cvt_pk_bf16_f32 v157, v78, v79
	v_cvt_pk_bf16_f32 v158, v72, v73
	v_cvt_pk_bf16_f32 v159, v74, v75
	global_store_dwordx4 v[216:217], v[156:159], off offset:256
	v_pk_mul_f32 v[238:239], v[88:89], v[88:89]
	v_pk_mul_f32 v[240:241], v[90:91], v[90:91]
	v_pk_fma_f32 v[238:239], v[84:85], v[84:85], v[238:239]
	v_pk_fma_f32 v[240:241], v[86:87], v[86:87], v[240:241]
	v_pk_fma_f32 v[238:239], v[76:77], v[76:77], v[238:239]
	v_pk_fma_f32 v[240:241], v[78:79], v[78:79], v[240:241]
	v_pk_fma_f32 v[238:239], v[72:73], v[72:73], v[238:239]
	v_pk_fma_f32 v[240:241], v[74:75], v[74:75], v[240:241]
	v_pk_add_f32 v[238:239], v[238:239], v[240:241]
	v_add_f32_e32 v216, v238, v239
	s_waitcnt vmcnt(14)
	v_lshlrev_b32_e32 v238, 16, v144
	v_and_b32_e32 v239, s28, v144
	v_lshlrev_b32_e32 v240, 16, v145
	v_and_b32_e32 v241, s28, v145
	v_lshlrev_b32_e32 v242, 16, v146
	v_and_b32_e32 v243, s28, v146
	v_lshlrev_b32_e32 v198, 16, v147
	v_and_b32_e32 v199, s28, v147
	v_pk_add_f32 v[64:65], v[64:65], v[238:239]
	v_pk_add_f32 v[66:67], v[66:67], v[240:241]
	v_pk_add_f32 v[60:61], v[60:61], v[242:243]
	v_pk_add_f32 v[62:63], v[62:63], v[198:199]
	v_cvt_pk_bf16_f32 v144, v64, v65
	v_cvt_pk_bf16_f32 v145, v66, v67
	v_cvt_pk_bf16_f32 v146, v60, v61
	v_cvt_pk_bf16_f32 v147, v62, v63
	global_store_dwordx4 v[218:219], v[144:147], off
	v_lshlrev_b32_e32 v238, 16, v132
	v_and_b32_e32 v239, s28, v132
	v_lshlrev_b32_e32 v240, 16, v133
	v_and_b32_e32 v241, s28, v133
	v_lshlrev_b32_e32 v242, 16, v134
	v_and_b32_e32 v243, s28, v134
	v_lshlrev_b32_e32 v198, 16, v135
	v_and_b32_e32 v199, s28, v135
	v_pk_add_f32 v[56:57], v[56:57], v[238:239]
	v_pk_add_f32 v[58:59], v[58:59], v[240:241]
	v_pk_add_f32 v[52:53], v[52:53], v[242:243]
	v_pk_add_f32 v[54:55], v[54:55], v[198:199]
	v_cvt_pk_bf16_f32 v132, v56, v57
	v_cvt_pk_bf16_f32 v133, v58, v59
	v_cvt_pk_bf16_f32 v134, v52, v53
	v_cvt_pk_bf16_f32 v135, v54, v55
	global_store_dwordx4 v[218:219], v[132:135], off offset:256
	v_pk_mul_f32 v[238:239], v[64:65], v[64:65]
	v_pk_mul_f32 v[240:241], v[66:67], v[66:67]
	v_pk_fma_f32 v[238:239], v[60:61], v[60:61], v[238:239]
	v_pk_fma_f32 v[240:241], v[62:63], v[62:63], v[240:241]
	v_pk_fma_f32 v[238:239], v[56:57], v[56:57], v[238:239]
	v_pk_fma_f32 v[240:241], v[58:59], v[58:59], v[240:241]
	v_pk_fma_f32 v[238:239], v[52:53], v[52:53], v[238:239]
	v_pk_fma_f32 v[240:241], v[54:55], v[54:55], v[240:241]
	v_pk_add_f32 v[238:239], v[238:239], v[240:241]
	v_add_f32_e32 v218, v238, v239
	s_waitcnt vmcnt(14)
; __device__ __forceinline__ unsigned cvtpk(float lo, float hi) { f32x2 v = {lo, hi}; bf16x2_t b = __builtin_convertvector(v, bf16x2_t); return __builtin_bit_cast(unsigned, b); }
;     __device__ __forceinline__ void operator()(const f32x4 (&acc)[2][2][4][2], const Unit& u, int wr, int wc, int fr, int fq) const {
;     ...
;                 for (int bj = 0; bj < 2; ++bj) {
;                     const u32x4 wv = w[ai][m][bj];
;                     f32x4 o0 = acc[ai][bj][m][0], o1 = acc[ai][bj][m][1];
;                     o0[0] += __builtin_bit_cast(float, wv.x << 16); o0[1] += __builtin_bit_cast(float, wv.x & 0xffff0000u); o0[2] += __builtin_bit_cast(float, wv.y << 16); o0[3] += __builtin_bit_cast(float, wv.y & 0xffff0000u);
;                     o1[0] += __builtin_bit_cast(float, wv.z << 16); o1[1] += __builtin_bit_cast(float, wv.z & 0xffff0000u); o1[2] += __builtin_bit_cast(float, wv.w << 16); o1[3] += __builtin_bit_cast(float, wv.w & 0xffff0000u);
;                     if (last) { *(f32x4*)(out + off + bj * HALF) = o0; *(f32x4*)(out + off + bj * HALF + 4) = o1; }
;                     else {
;                         u32x4 v; v.x = cvtpk(o0[0], o0[1]); v.y = cvtpk(o0[2], o0[3]); v.z = cvtpk(o1[0], o1[1]); v.w = cvtpk(o1[2], o1[3]);
;                         *(u32x4*)(xb + off + bj * HALF) = v;
;                         ss += (o0[0] * o0[0] + o0[1] * o0[1]) + (o0[2] * o0[2] + o0[3] * o0[3]) + (o1[0] * o1[0] + o1[1] * o1[1]) + (o1[2] * o1[2] + o1[3] * o1[3]);
;                     }
;                 }
;                 if (!last) {
;                     ss += __shfl_xor(ss, 16); ss += __shfl_xor(ss, 32);
;                     if (fq == 0) ssq_out[(size_t)row * 16 + 4 * u.pn + wc] = ss;
;                 }
	v_lshlrev_b32_e32 v238, 16, v120
	v_and_b32_e32 v239, s28, v120
	v_lshlrev_b32_e32 v240, 16, v121
	v_and_b32_e32 v241, s28, v121
	v_lshlrev_b32_e32 v242, 16, v122
	v_and_b32_e32 v243, s28, v122
	v_lshlrev_b32_e32 v198, 16, v123
	v_and_b32_e32 v199, s28, v123
	v_pk_add_f32 v[48:49], v[48:49], v[238:239]
	v_pk_add_f32 v[50:51], v[50:51], v[240:241]
	v_pk_add_f32 v[44:45], v[44:45], v[242:243]
	v_pk_add_f32 v[46:47], v[46:47], v[198:199]
	v_cvt_pk_bf16_f32 v120, v48, v49
	v_cvt_pk_bf16_f32 v121, v50, v51
	v_cvt_pk_bf16_f32 v122, v44, v45
	v_cvt_pk_bf16_f32 v123, v46, v47
	global_store_dwordx4 v[220:221], v[120:123], off
	v_lshlrev_b32_e32 v238, 16, v112
	v_and_b32_e32 v239, s28, v112
	v_lshlrev_b32_e32 v240, 16, v113
	v_and_b32_e32 v241, s28, v113
	v_lshlrev_b32_e32 v242, 16, v114
	v_and_b32_e32 v243, s28, v114
	v_lshlrev_b32_e32 v198, 16, v115
	v_and_b32_e32 v199, s28, v115
	v_pk_add_f32 v[40:41], v[40:41], v[238:239]
	v_pk_add_f32 v[42:43], v[42:43], v[240:241]
	v_pk_add_f32 v[36:37], v[36:37], v[242:243]
	v_pk_add_f32 v[38:39], v[38:39], v[198:199]
	v_cvt_pk_bf16_f32 v112, v40, v41
	v_cvt_pk_bf16_f32 v113, v42, v43
	v_cvt_pk_bf16_f32 v114, v36, v37
	v_cvt_pk_bf16_f32 v115, v38, v39
	global_store_dwordx4 v[220:221], v[112:115], off offset:256
	v_pk_mul_f32 v[238:239], v[48:49], v[48:49]
	v_pk_mul_f32 v[240:241], v[50:51], v[50:51]
	v_pk_fma_f32 v[238:239], v[44:45], v[44:45], v[238:239]
	v_pk_fma_f32 v[240:241], v[46:47], v[46:47], v[240:241]
	v_pk_fma_f32 v[238:239], v[40:41], v[40:41], v[238:239]
	v_pk_fma_f32 v[240:241], v[42:43], v[42:43], v[240:241]
	v_pk_fma_f32 v[238:239], v[36:37], v[36:37], v[238:239]
	v_pk_fma_f32 v[240:241], v[38:39], v[38:39], v[240:241]
	v_pk_add_f32 v[238:239], v[238:239], v[240:241]
	v_add_f32_e32 v220, v238, v239
	s_waitcnt vmcnt(14)
	v_lshlrev_b32_e32 v238, 16, v100
	v_and_b32_e32 v239, s28, v100
	v_lshlrev_b32_e32 v240, 16, v101
	v_and_b32_e32 v241, s28, v101
	v_lshlrev_b32_e32 v242, 16, v102
	v_and_b32_e32 v243, s28, v102
	v_lshlrev_b32_e32 v198, 16, v103
	v_and_b32_e32 v199, s28, v103
	v_pk_add_f32 v[32:33], v[32:33], v[238:239]
	v_pk_add_f32 v[34:35], v[34:35], v[240:241]
	v_pk_add_f32 v[28:29], v[28:29], v[242:243]
	v_pk_add_f32 v[30:31], v[30:31], v[198:199]
	v_cvt_pk_bf16_f32 v100, v32, v33
	v_cvt_pk_bf16_f32 v101, v34, v35
	v_cvt_pk_bf16_f32 v102, v28, v29
	v_cvt_pk_bf16_f32 v103, v30, v31
	global_store_dwordx4 v[222:223], v[100:103], off
	v_lshlrev_b32_e32 v238, 16, v92
	v_and_b32_e32 v239, s28, v92
	v_lshlrev_b32_e32 v240, 16, v93
	v_and_b32_e32 v241, s28, v93
	v_lshlrev_b32_e32 v242, 16, v94
	v_and_b32_e32 v243, s28, v94
	v_lshlrev_b32_e32 v198, 16, v95
	v_and_b32_e32 v199, s28, v95
	v_pk_add_f32 v[24:25], v[24:25], v[238:239]
	v_pk_add_f32 v[26:27], v[26:27], v[240:241]
	v_pk_add_f32 v[20:21], v[20:21], v[242:243]
	v_pk_add_f32 v[22:23], v[22:23], v[198:199]
	v_cvt_pk_bf16_f32 v92, v24, v25
	v_cvt_pk_bf16_f32 v93, v26, v27
	v_cvt_pk_bf16_f32 v94, v20, v21
	v_cvt_pk_bf16_f32 v95, v22, v23
	global_store_dwordx4 v[222:223], v[92:95], off offset:256
	v_pk_mul_f32 v[238:239], v[32:33], v[32:33]
	v_pk_mul_f32 v[240:241], v[34:35], v[34:35]
	v_pk_fma_f32 v[238:239], v[28:29], v[28:29], v[238:239]
	v_pk_fma_f32 v[240:241], v[30:31], v[30:31], v[240:241]
	v_pk_fma_f32 v[238:239], v[24:25], v[24:25], v[238:239]
	v_pk_fma_f32 v[240:241], v[26:27], v[26:27], v[240:241]
	v_pk_fma_f32 v[238:239], v[20:21], v[20:21], v[238:239]
	v_pk_fma_f32 v[240:241], v[22:23], v[22:23], v[240:241]
	v_pk_add_f32 v[238:239], v[238:239], v[240:241]
	v_add_f32_e32 v222, v238, v239
	s_waitcnt vmcnt(14)
	v_lshlrev_b32_e32 v238, 16, v80
	v_and_b32_e32 v239, s28, v80
	v_lshlrev_b32_e32 v240, 16, v81
	v_and_b32_e32 v241, s28, v81
	v_lshlrev_b32_e32 v242, 16, v82
	v_and_b32_e32 v243, s28, v82
	v_lshlrev_b32_e32 v198, 16, v83
	v_and_b32_e32 v199, s28, v83
	v_pk_add_f32 v[16:17], v[16:17], v[238:239]
	v_pk_add_f32 v[18:19], v[18:19], v[240:241]
	v_pk_add_f32 v[12:13], v[12:13], v[242:243]
	v_pk_add_f32 v[14:15], v[14:15], v[198:199]
	v_cvt_pk_bf16_f32 v80, v16, v17
	v_cvt_pk_bf16_f32 v81, v18, v19
	v_cvt_pk_bf16_f32 v82, v12, v13
	v_cvt_pk_bf16_f32 v83, v14, v15
	global_store_dwordx4 v[224:225], v[80:83], off
	v_lshlrev_b32_e32 v238, 16, v68
	v_and_b32_e32 v239, s28, v68
	v_lshlrev_b32_e32 v240, 16, v69
	v_and_b32_e32 v241, s28, v69
	v_lshlrev_b32_e32 v242, 16, v70
	v_and_b32_e32 v243, s28, v70
	v_lshlrev_b32_e32 v198, 16, v71
	v_and_b32_e32 v199, s28, v71
	v_pk_add_f32 v[8:9], v[8:9], v[238:239]
	v_pk_add_f32 v[10:11], v[10:11], v[240:241]
	v_pk_add_f32 v[4:5], v[4:5], v[242:243]
	v_pk_add_f32 v[6:7], v[6:7], v[198:199]
	v_cvt_pk_bf16_f32 v68, v8, v9
	v_cvt_pk_bf16_f32 v69, v10, v11
	v_cvt_pk_bf16_f32 v70, v4, v5
	v_cvt_pk_bf16_f32 v71, v6, v7
	global_store_dwordx4 v[224:225], v[68:71], off offset:256
	v_pk_mul_f32 v[238:239], v[16:17], v[16:17]
	v_pk_mul_f32 v[240:241], v[18:19], v[18:19]
	v_pk_fma_f32 v[238:239], v[12:13], v[12:13], v[238:239]
	v_pk_fma_f32 v[240:241], v[14:15], v[14:15], v[240:241]
	v_pk_fma_f32 v[238:239], v[8:9], v[8:9], v[238:239]
	v_pk_fma_f32 v[240:241], v[10:11], v[10:11], v[240:241]
	v_pk_fma_f32 v[238:239], v[4:5], v[4:5], v[238:239]
	v_pk_fma_f32 v[240:241], v[6:7], v[6:7], v[240:241]
	v_pk_add_f32 v[238:239], v[238:239], v[240:241]
	v_add_f32_e32 v224, v238, v239
	s_nop 1
	v_permlane32_swap_b32_e32 v210, v212
	v_permlane32_swap_b32_e32 v214, v216
	v_permlane32_swap_b32_e32 v218, v220
	v_permlane32_swap_b32_e32 v222, v224
	v_add_f32_e32 v210, v210, v212
	v_add_f32_e32 v214, v214, v216
	v_add_f32_e32 v218, v218, v220
	v_add_f32_e32 v222, v222, v224
	s_nop 1
	v_permlane16_swap_b32_e32 v210, v214
	v_permlane16_swap_b32_e32 v218, v222
	v_add_f32_e32 v210, v210, v214
	v_add_f32_e32 v218, v218, v222
	v_bfe_u32 v238, v250, 4, 1
	v_bfe_u32 v239, v250, 5, 1
	v_lshl_or_b32 v238, v238, 1, v239
	v_lshlrev_b32_e32 v240, 6, v208
	v_lshl_add_u32 v240, v238, 10, v240
	s_lshl_b32 s29, s52, 4
	s_lshl_b32 s27, s46, 2
	s_add_i32 s29, s29, s27
	v_add_u32_e32 v240, s29, v240
	v_mov_b32_e32 v241, v2
	v_lshl_add_u64 v[240:241], s[14:15], 0, v[240:241]
	s_mov_b32 s100, 0x2000
	v_lshl_add_u64 v[242:243], v[240:241], 0, s[100:101]
	global_store_dword v[240:241], v210, off
	global_store_dword v[242:243], v218, off
	s_and_b64 vcc, exec, s[6:7]
	s_mov_b64 s[6:7], -1
	s_cbranch_vccnz .LBB0_468
	s_branch .LBB0_580
